# lever 4 in the attention k-tile loop: one static priority raise for waves 0-3, the four per-segment s_setprio flips removed (raising waves 4-7 instead costs +2 percent)
# speedup vs baseline: 1.0024x; 1.0012x over previous
.LBB0_213:
	s_or_b64 exec, exec, s[22:23]
	s_xor_b64 s[22:23], s[10:11], -1
	s_add_i32 s10, 0, 0x10000
	v_lshl_add_u32 v192, v0, 2, s10
	v_cmp_eq_u32_e64 s[10:11], 0, v0
	v_add_u32_e32 v230, s39, v0
	v_mad_i64_i32 v[0:1], s[26:27], v1, s67, 0
	v_lshl_or_b32 v0, v2, 4, v0
	v_mov_b32_e32 v14, v129
	v_mov_b32_e32 v15, v129
	s_lshl_b32 s44, s28, 1
	v_lshl_add_u64 v[180:181], s[20:21], 0, v[0:1]
	v_mov_b32_e32 v0, v129
	v_mov_b32_e32 v1, v129
	v_mov_b32_e32 v2, v129
	v_mov_b32_e32 v3, v129
	v_mov_b32_e32 v4, v129
	s_waitcnt lgkmcnt(0)
	v_mov_b32_e32 v5, v129
	v_mov_b32_e32 v6, v129
	v_mov_b32_e32 v7, v129
	v_mov_b32_e32 v8, v129
	v_mov_b32_e32 v9, v129
	v_mov_b32_e32 v10, v129
	v_mov_b32_e32 v11, v129
	v_mov_b32_e32 v12, v129
	v_mov_b32_e32 v13, v129
	v_mov_b64_e32 v[30:31], v[14:15]
	v_mov_b64_e32 v[46:47], v[14:15]
	v_mov_b64_e32 v[62:63], v[14:15]
	s_add_i32 s44, s44, 2
	s_or_b32 s45, s42, 31
	s_lshl_b32 s46, s41, 3
	s_mov_b32 s47, 0
	v_and_b32_e32 v221, 31, v183
	v_lshrrev_b32_e32 v222, 5, v183
	v_and_b32_e32 v223, 3, v183
	v_lshlrev_b32_e32 v223, 2, v223
	v_bfe_u32 v224, v183, 2, 2
	v_or_b32_e32 v223, v223, v224
	v_add_u32_e32 v225, s46, v222
	v_lshlrev_b32_e32 v226, 8, v221
	v_xor_b32_e32 v227, v225, v223
	v_lshl_add_u32 v209, v227, 4, v226
	v_add_u32_e32 v227, 2, v225
	v_xor_b32_e32 v227, v227, v223
	v_lshl_add_u32 v210, v227, 4, v226
	v_add_u32_e32 v227, 4, v225
	v_xor_b32_e32 v227, v227, v223
	v_lshl_add_u32 v211, v227, 4, v226
	v_add_u32_e32 v227, 6, v225
	v_xor_b32_e32 v227, v227, v223
	v_lshl_add_u32 v212, v227, 4, v226
	v_lshrrev_b32_e32 v227, 3, v183
	v_bfe_u32 v228, v183, 1, 1
	v_and_or_b32 v227, v227, 2, v228
	v_and_b32_e32 v228, 1, v183
	v_lshlrev_b32_e32 v228, 3, v228
	v_lshl_or_b32 v229, v222, 2, v224
	v_lshl_add_u32 v228, v229, 8, v228
	v_xor_b32_e32 v229, v227, v222
	v_lshl_add_u32 v229, v229, 4, v228
	v_lshl_add_u32 v213, v224, 6, v229
	v_xor_b32_e32 v193, 1, v224
	v_lshl_add_u32 v215, v193, 6, v229
	v_xor_b32_e32 v193, 2, v224
	v_lshl_add_u32 v217, v193, 6, v229
	v_xor_b32_e32 v193, 3, v224
	v_lshl_add_u32 v219, v193, 6, v229
	v_add_u32_e32 v229, 2, v222
	v_xor_b32_e32 v229, v227, v229
	v_lshl_add_u32 v229, v229, 4, v228
	v_add_u32_e32 v229, 0x800, v229
	v_lshl_add_u32 v214, v224, 6, v229
	v_xor_b32_e32 v193, 1, v224
	v_lshl_add_u32 v216, v193, 6, v229
	v_xor_b32_e32 v193, 2, v224
	v_lshl_add_u32 v218, v193, 6, v229
	v_xor_b32_e32 v193, 3, v224
	v_lshl_add_u32 v220, v193, 6, v229
	s_addk_i32 s48, 0x80
	v_mov_b32_e32 v232, 0
	v_mov_b32_e32 v235, 0xf149f2ca
	v_mov_b64_e32 v[28:29], v[12:13]
	v_mov_b64_e32 v[26:27], v[10:11]
	v_mov_b64_e32 v[24:25], v[8:9]
	v_mov_b64_e32 v[22:23], v[6:7]
	v_mov_b64_e32 v[20:21], v[4:5]
	v_mov_b64_e32 v[18:19], v[2:3]
	v_mov_b64_e32 v[16:17], v[0:1]
	v_mov_b64_e32 v[44:45], v[12:13]
	v_mov_b64_e32 v[42:43], v[10:11]
	v_mov_b64_e32 v[40:41], v[8:9]
	v_mov_b64_e32 v[38:39], v[6:7]
	v_mov_b64_e32 v[36:37], v[4:5]
	v_mov_b64_e32 v[34:35], v[2:3]
	v_mov_b64_e32 v[32:33], v[0:1]
	v_mov_b64_e32 v[60:61], v[12:13]
	v_mov_b64_e32 v[58:59], v[10:11]
	v_mov_b64_e32 v[56:57], v[8:9]
	v_mov_b64_e32 v[54:55], v[6:7]
	v_mov_b64_e32 v[52:53], v[4:5]
	v_mov_b64_e32 v[50:51], v[2:3]
	v_mov_b64_e32 v[48:49], v[0:1]
	s_mov_b32 s28, 0
	s_barrier
	v_readfirstlane_b32 s34, v163
	s_nop 3
	s_cmp_ge_u32 s34, 0x100
	s_cbranch_scc1 .Lattn_prio_done
	s_setprio 1
.Lattn_prio_done:
	.p2align 6

.LBB0_216:
	s_and_b32 s50, s28, 1
	s_cmp_gt_i32 s47, s45
	s_cbranch_scc1 .LBB0_228
	v_mov_b32_e32 v233, v183
	s_lshl_b32 s28, s50, 15
	s_add_i32 s51, s28, 0
	v_ashrrev_i32_e32 v234, 5, v233
	v_lshlrev_b32_e32 v237, 2, v233
	v_bfe_u32 v231, v233, 2, 2
	s_cmp_eq_u32 s50, 0
	s_cbranch_scc1 .Lattn_qk_b0
	ds_read_b128 v[64:67], v209 offset:32768
	ds_read_b128 v[68:71], v210 offset:32768
	ds_read_b128 v[72:75], v211 offset:32768
	ds_read_b128 v[76:79], v212 offset:32768
	ds_read_b128 v[112:115], v209 offset:40960
	ds_read_b128 v[116:119], v210 offset:40960
	ds_read_b128 v[120:123], v211 offset:40960
	ds_read_b128 v[124:127], v212 offset:40960
	s_waitcnt lgkmcnt(7)
	v_mfma_f32_32x32x16_bf16 v[96:111], v[64:67], v[130:133], 0
	s_waitcnt lgkmcnt(6)
	v_mfma_f32_32x32x16_bf16 v[96:111], v[68:71], v[134:137], v[96:111]
	s_waitcnt lgkmcnt(5)
	v_mfma_f32_32x32x16_bf16 v[96:111], v[72:75], v[138:141], v[96:111]
	s_waitcnt lgkmcnt(4)
	v_mfma_f32_32x32x16_bf16 v[96:111], v[76:79], v[142:145], v[96:111]
	s_waitcnt lgkmcnt(3)
	v_mfma_f32_32x32x16_bf16 v[80:95], v[112:115], v[130:133], 0
	s_waitcnt lgkmcnt(2)
	v_mfma_f32_32x32x16_bf16 v[80:95], v[116:119], v[134:137], v[80:95]
	s_waitcnt lgkmcnt(1)
	v_mfma_f32_32x32x16_bf16 v[80:95], v[120:123], v[138:141], v[80:95]
	s_waitcnt lgkmcnt(0)
	v_mfma_f32_32x32x16_bf16 v[80:95], v[124:127], v[142:145], v[80:95]
	s_branch .Lattn_qk_join
	.p2align 6

.Lattn_qk_join:
	s_lshl_b32 s28, s50, 2
	s_add_i32 s28, s28, 0
	s_add_i32 s28, s28, 0x10410
	v_mov_b32_e32 v64, s28
	ds_read_b32 v64, v64
	s_waitcnt lgkmcnt(0)
	v_readfirstlane_b32 s28, v64
	s_sub_i32 s28, s43, s28
	s_cmpk_gt_i32 s28, 0x7f
	s_cselect_b64 s[30:31], -1, 0
	s_cmpk_lt_i32 s28, 0x80
	s_cselect_b64 s[34:35], -1, 0
	s_add_i32 s28, s47, 63
	s_cmp_gt_i32 s28, s42
	s_cselect_b64 s[28:29], -1, 0
	s_or_b64 s[52:53], s[34:35], s[28:29]
	s_mov_b64 s[34:35], -1
	s_and_b64 vcc, exec, s[52:53]
	s_cbranch_vccnz .LBB0_219
	v_max_f32_e32 v64, v97, v97
	v_max_f32_e32 v65, v96, v96
	v_max_f32_e32 v64, v65, v64
	v_max3_f32 v64, v64, v98, v99
	v_max3_f32 v64, v64, v100, v101
	v_max3_f32 v64, v64, v102, v103
	v_max3_f32 v64, v64, v104, v105
	v_max3_f32 v64, v64, v106, v107
	v_max3_f32 v64, v64, v108, v109
	v_max3_f32 v64, v64, v110, v111
	v_max3_f32 v64, v64, v80, v81
	v_max3_f32 v64, v64, v82, v83
	v_max3_f32 v64, v64, v84, v85
	v_max3_f32 v64, v64, v86, v87
	v_max3_f32 v64, v64, v88, v89
	v_max3_f32 v64, v64, v90, v91
	v_max3_f32 v64, v64, v92, v93
	v_max3_f32 v64, v64, v94, v95
	v_xor_b32_e32 v254, 0x80, v237
	ds_bpermute_b32 v65, v254, v64
	v_mov_b32_e32 v66, s89
	ds_read_b32 v66, v66
	v_mul_f32_e32 v113, 0x3e38aa3b, v95
	s_mov_b64 s[34:35], 0
	s_waitcnt lgkmcnt(1)
	v_max_f32_e32 v65, v65, v65
	v_max_f32_e32 v64, v64, v65
	s_waitcnt lgkmcnt(0)
	v_fmamk_f32 v64, v64, 0x3e38aa3b, v66
	v_max_f32_e32 v65, v235, v235
	v_max_f32_e32 v236, v65, v64
	v_sub_f32_e32 v79, v66, v236
	v_fmamk_f32 v64, v96, 0x3e38aa3b, v79
	v_exp_f32_e32 v246, v64
	v_fmamk_f32 v64, v97, 0x3e38aa3b, v79
	v_exp_f32_e32 v247, v64
	v_fmamk_f32 v64, v98, 0x3e38aa3b, v79
	v_exp_f32_e32 v248, v64
	v_fmamk_f32 v64, v99, 0x3e38aa3b, v79
	v_exp_f32_e32 v249, v64
	v_fmamk_f32 v65, v100, 0x3e38aa3b, v79
	v_add_f32_e32 v64, 0, v246
	v_exp_f32_e32 v250, v65
	v_fmamk_f32 v65, v101, 0x3e38aa3b, v79
	v_add_f32_e32 v64, v247, v64
	v_exp_f32_e32 v251, v65
	v_fmamk_f32 v65, v102, 0x3e38aa3b, v79
	v_add_f32_e32 v64, v248, v64
	v_exp_f32_e32 v252, v65
	v_fmamk_f32 v65, v103, 0x3e38aa3b, v79
	v_add_f32_e32 v64, v249, v64
	v_exp_f32_e32 v253, v65
	v_fmamk_f32 v65, v104, 0x3e38aa3b, v79
	v_add_f32_e32 v64, v250, v64
	v_exp_f32_e32 v238, v65
	v_fmamk_f32 v65, v105, 0x3e38aa3b, v79
	v_add_f32_e32 v64, v251, v64
	v_exp_f32_e32 v239, v65
	v_fmamk_f32 v65, v106, 0x3e38aa3b, v79
	v_add_f32_e32 v64, v252, v64
	v_exp_f32_e32 v240, v65
	v_fmamk_f32 v65, v107, 0x3e38aa3b, v79
	v_add_f32_e32 v64, v253, v64
	v_exp_f32_e32 v241, v65
	v_fmamk_f32 v65, v108, 0x3e38aa3b, v79
	v_add_f32_e32 v64, v238, v64
	v_exp_f32_e32 v242, v65
	v_fmamk_f32 v65, v109, 0x3e38aa3b, v79
	v_add_f32_e32 v64, v239, v64
	v_exp_f32_e32 v243, v65
	v_fmamk_f32 v65, v110, 0x3e38aa3b, v79
	v_add_f32_e32 v64, v240, v64
	v_exp_f32_e32 v244, v65
	v_fmamk_f32 v65, v111, 0x3e38aa3b, v79
	v_add_f32_e32 v64, v241, v64
	v_exp_f32_e32 v245, v65
	v_add_f32_e32 v64, v242, v64
	v_add_f32_e32 v64, v243, v64
	v_add_f32_e32 v64, v244, v64
	v_add_f32_e32 v68, v245, v64
	v_fmamk_f32 v64, v80, 0x3e38aa3b, v79
	v_exp_f32_e32 v64, v64
	v_fmamk_f32 v65, v81, 0x3e38aa3b, v79
	v_exp_f32_e32 v65, v65
	v_fmamk_f32 v66, v82, 0x3e38aa3b, v79
	v_exp_f32_e32 v66, v66
	v_fmamk_f32 v67, v83, 0x3e38aa3b, v79
	v_exp_f32_e32 v67, v67
	v_add_f32_e32 v68, v64, v68
	v_add_f32_e32 v68, v65, v68
	v_add_f32_e32 v68, v66, v68
	v_add_f32_e32 v72, v67, v68
	v_fmamk_f32 v68, v84, 0x3e38aa3b, v79
	v_exp_f32_e32 v68, v68
	v_fmamk_f32 v69, v85, 0x3e38aa3b, v79
	v_exp_f32_e32 v69, v69
	v_fmamk_f32 v70, v86, 0x3e38aa3b, v79
	v_exp_f32_e32 v70, v70
	v_fmamk_f32 v71, v87, 0x3e38aa3b, v79
	v_exp_f32_e32 v71, v71
	v_add_f32_e32 v72, v68, v72
	v_add_f32_e32 v72, v69, v72
	v_add_f32_e32 v72, v70, v72
	v_add_f32_e32 v76, v71, v72
	v_fmamk_f32 v72, v88, 0x3e38aa3b, v79
	v_exp_f32_e32 v72, v72
	v_fmamk_f32 v73, v89, 0x3e38aa3b, v79
	v_exp_f32_e32 v73, v73
	v_fmamk_f32 v74, v90, 0x3e38aa3b, v79
	v_exp_f32_e32 v74, v74
	v_fmamk_f32 v75, v91, 0x3e38aa3b, v79
	v_exp_f32_e32 v75, v75
	v_add_f32_e32 v76, v72, v76
	v_add_f32_e32 v76, v73, v76
	v_add_f32_e32 v76, v74, v76
	v_add_f32_e32 v112, v75, v76
	v_fmamk_f32 v76, v92, 0x3e38aa3b, v79
	v_exp_f32_e32 v76, v76
	v_fmamk_f32 v77, v93, 0x3e38aa3b, v79
	v_exp_f32_e32 v77, v77
	v_fmamk_f32 v78, v94, 0x3e38aa3b, v79
	v_exp_f32_e32 v78, v78
	v_add_f32_e32 v112, v76, v112
	v_add_f32_e32 v112, v77, v112
	v_pk_add_f32 v[112:113], v[78:79], v[112:113]

.LBB0_227:
	s_waitcnt lgkmcnt(0)
	v_add_f32_e32 v81, v81, v82
	v_fmac_f32_e32 v81, v232, v80
	s_cmp_eq_u32 s50, 0
	s_cbranch_scc1 .Lattn_pv_b0
	ds_read_b64_tr_b16 v[92:93], v213 offset:49152
	ds_read_b64_tr_b16 v[94:95], v214 offset:49152
	ds_read_b64_tr_b16 v[96:97], v215 offset:49152
	ds_read_b64_tr_b16 v[98:99], v216 offset:49152
	ds_read_b64_tr_b16 v[100:101], v217 offset:49152
	ds_read_b64_tr_b16 v[102:103], v218 offset:49152
	ds_read_b64_tr_b16 v[104:105], v219 offset:49152
	ds_read_b64_tr_b16 v[106:107], v220 offset:49152
	ds_read_b64_tr_b16 v[108:109], v213 offset:53248
	ds_read_b64_tr_b16 v[110:111], v214 offset:53248
	ds_read_b64_tr_b16 v[112:113], v215 offset:53248
	ds_read_b64_tr_b16 v[114:115], v216 offset:53248
	v_cvt_pk_bf16_f32 v82, v246, v247
	v_cvt_pk_bf16_f32 v83, v248, v249
	v_cvt_pk_bf16_f32 v84, v250, v251
	v_cvt_pk_bf16_f32 v85, v252, v253
	s_nop 1
	s_waitcnt lgkmcnt(10)
	v_mfma_f32_32x32x16_bf16 v[48:63], v[92:95], v[82:85], v[48:63]
	v_cvt_pk_bf16_f32 v86, v238, v239
	v_cvt_pk_bf16_f32 v87, v240, v241
	v_cvt_pk_bf16_f32 v88, v242, v243
	v_cvt_pk_bf16_f32 v89, v244, v245
	ds_read_b64_tr_b16 v[116:117], v217 offset:53248
	ds_read_b64_tr_b16 v[118:119], v218 offset:53248
	s_waitcnt lgkmcnt(10)
	v_mfma_f32_32x32x16_bf16 v[32:47], v[96:99], v[82:85], v[32:47]
	ds_read_b64_tr_b16 v[120:121], v219 offset:53248
	ds_read_b64_tr_b16 v[122:123], v220 offset:53248
	s_waitcnt lgkmcnt(10)
	v_mfma_f32_32x32x16_bf16 v[16:31], v[100:103], v[82:85], v[16:31]
	ds_read_b64_tr_b16 v[92:93], v213 offset:57344
	ds_read_b64_tr_b16 v[94:95], v214 offset:57344
	s_waitcnt lgkmcnt(10)
	v_mfma_f32_32x32x16_bf16 v[0:15], v[104:107], v[82:85], v[0:15]
	ds_read_b64_tr_b16 v[96:97], v215 offset:57344
	ds_read_b64_tr_b16 v[98:99], v216 offset:57344
	s_waitcnt lgkmcnt(10)
	v_mfma_f32_32x32x16_bf16 v[48:63], v[108:111], v[86:89], v[48:63]
	v_cvt_pk_bf16_f32 v82, v64, v65
	v_cvt_pk_bf16_f32 v83, v66, v67
	v_cvt_pk_bf16_f32 v84, v68, v69
	v_cvt_pk_bf16_f32 v85, v70, v71
	ds_read_b64_tr_b16 v[100:101], v217 offset:57344
	ds_read_b64_tr_b16 v[102:103], v218 offset:57344
	s_waitcnt lgkmcnt(10)
	v_mfma_f32_32x32x16_bf16 v[32:47], v[112:115], v[86:89], v[32:47]
	ds_read_b64_tr_b16 v[104:105], v219 offset:57344
	ds_read_b64_tr_b16 v[106:107], v220 offset:57344
	s_waitcnt lgkmcnt(10)
	v_mfma_f32_32x32x16_bf16 v[16:31], v[116:119], v[86:89], v[16:31]
	ds_read_b64_tr_b16 v[108:109], v213 offset:61440
	ds_read_b64_tr_b16 v[110:111], v214 offset:61440
	s_waitcnt lgkmcnt(10)
	v_mfma_f32_32x32x16_bf16 v[0:15], v[120:123], v[86:89], v[0:15]
	ds_read_b64_tr_b16 v[112:113], v215 offset:61440
	ds_read_b64_tr_b16 v[114:115], v216 offset:61440
	s_waitcnt lgkmcnt(10)
	v_mfma_f32_32x32x16_bf16 v[48:63], v[92:95], v[82:85], v[48:63]
	v_cvt_pk_bf16_f32 v86, v72, v73
	v_cvt_pk_bf16_f32 v87, v74, v75
	v_cvt_pk_bf16_f32 v88, v76, v77
	v_cvt_pk_bf16_f32 v89, v78, v79
	ds_read_b64_tr_b16 v[116:117], v217 offset:61440
	ds_read_b64_tr_b16 v[118:119], v218 offset:61440
	s_waitcnt lgkmcnt(10)
	v_mfma_f32_32x32x16_bf16 v[32:47], v[96:99], v[82:85], v[32:47]
	ds_read_b64_tr_b16 v[120:121], v219 offset:61440
	ds_read_b64_tr_b16 v[122:123], v220 offset:61440
	s_waitcnt lgkmcnt(10)
	v_mfma_f32_32x32x16_bf16 v[16:31], v[100:103], v[82:85], v[16:31]
	s_waitcnt lgkmcnt(8)
	v_mfma_f32_32x32x16_bf16 v[0:15], v[104:107], v[82:85], v[0:15]
	s_waitcnt lgkmcnt(6)
	v_mfma_f32_32x32x16_bf16 v[48:63], v[108:111], v[86:89], v[48:63]
	s_waitcnt lgkmcnt(4)
	v_mfma_f32_32x32x16_bf16 v[32:47], v[112:115], v[86:89], v[32:47]
	s_waitcnt lgkmcnt(2)
	v_mfma_f32_32x32x16_bf16 v[16:31], v[116:119], v[86:89], v[16:31]
	s_waitcnt lgkmcnt(0)
	v_mfma_f32_32x32x16_bf16 v[0:15], v[120:123], v[86:89], v[0:15]
	s_branch .Lattn_pv_join
	.p2align 6

.Lattn_pv_join:
	v_mov_b32_e32 v232, v81
	s_andn2_b64 vcc, exec, s[26:27]
	s_cbranch_vccz .LBB0_229
	s_branch .LBB0_233

.LBB0_237:
	s_setprio 0
	v_div_scale_f32 v64, s[8:9], v232, v232, 1.0
	v_rcp_f32_e32 v65, v64
	v_div_scale_f32 v66, vcc, 1.0, v232, 1.0
	s_cmp_eq_u32 s41, 0
	v_fma_f32 v67, -v64, v65, 1.0
	v_fmac_f32_e32 v65, v67, v65
	v_mul_f32_e32 v67, v66, v65
	v_fma_f32 v68, -v64, v67, v66
	v_fmac_f32_e32 v67, v68, v65
	v_fma_f32 v64, -v64, v67, v66
	v_div_fmas_f32 v64, v64, v65, v67
	s_cselect_b64 s[8:9], -1, 0
	v_div_fixup_f32 v64, v64, v232, 1.0
	s_and_b64 vcc, exec, s[8:9]
	s_cbranch_vccnz .LBB0_239
	s_lshl_b32 s10, s40, 14
	s_add_i32 s10, s10, 0
	v_mul_f32_e32 v65, v48, v64
	v_lshl_add_u32 v66, v183, 2, s10
	v_mul_f32_e32 v67, v49, v64
	ds_write2st64_b32 v66, v65, v67 offset1:1
	v_mul_f32_e32 v65, v50, v64
	v_mul_f32_e32 v67, v51, v64
	ds_write2st64_b32 v66, v65, v67 offset0:2 offset1:3
	v_mul_f32_e32 v65, v52, v64
	v_mul_f32_e32 v67, v53, v64
	ds_write2st64_b32 v66, v65, v67 offset0:4 offset1:5
	v_mul_f32_e32 v65, v54, v64
	v_mul_f32_e32 v67, v55, v64
	ds_write2st64_b32 v66, v65, v67 offset0:6 offset1:7
	v_mul_f32_e32 v65, v56, v64
	v_mul_f32_e32 v67, v57, v64
	ds_write2st64_b32 v66, v65, v67 offset0:8 offset1:9
	v_mul_f32_e32 v65, v58, v64
	v_mul_f32_e32 v67, v59, v64
	ds_write2st64_b32 v66, v65, v67 offset0:10 offset1:11
	v_mul_f32_e32 v65, v60, v64
	v_mul_f32_e32 v67, v61, v64
	ds_write2st64_b32 v66, v65, v67 offset0:12 offset1:13
	v_mul_f32_e32 v65, v62, v64
	v_mul_f32_e32 v67, v63, v64
	ds_write2st64_b32 v66, v65, v67 offset0:14 offset1:15
	v_mul_f32_e32 v65, v32, v64
	v_mul_f32_e32 v67, v33, v64
	ds_write2st64_b32 v66, v65, v67 offset0:16 offset1:17
	v_mul_f32_e32 v65, v34, v64
	v_mul_f32_e32 v67, v35, v64
	ds_write2st64_b32 v66, v65, v67 offset0:18 offset1:19
	v_mul_f32_e32 v65, v36, v64
	v_mul_f32_e32 v67, v37, v64
	ds_write2st64_b32 v66, v65, v67 offset0:20 offset1:21
	v_mul_f32_e32 v65, v38, v64
	v_mul_f32_e32 v67, v39, v64
	ds_write2st64_b32 v66, v65, v67 offset0:22 offset1:23
	v_mul_f32_e32 v65, v40, v64
	v_mul_f32_e32 v67, v41, v64
	ds_write2st64_b32 v66, v65, v67 offset0:24 offset1:25
	v_mul_f32_e32 v65, v42, v64
	v_mul_f32_e32 v67, v43, v64
	ds_write2st64_b32 v66, v65, v67 offset0:26 offset1:27
	v_mul_f32_e32 v65, v44, v64
	v_mul_f32_e32 v67, v45, v64
	ds_write2st64_b32 v66, v65, v67 offset0:28 offset1:29
	v_mul_f32_e32 v65, v46, v64
	v_mul_f32_e32 v67, v47, v64
	ds_write2st64_b32 v66, v65, v67 offset0:30 offset1:31
	v_mul_f32_e32 v65, v16, v64
	v_mul_f32_e32 v67, v17, v64
	ds_write2st64_b32 v66, v65, v67 offset0:32 offset1:33
	v_mul_f32_e32 v65, v18, v64
	v_mul_f32_e32 v67, v19, v64
	ds_write2st64_b32 v66, v65, v67 offset0:34 offset1:35
	v_mul_f32_e32 v65, v20, v64
	v_mul_f32_e32 v67, v21, v64
	ds_write2st64_b32 v66, v65, v67 offset0:36 offset1:37
	v_mul_f32_e32 v65, v22, v64
	v_mul_f32_e32 v67, v23, v64
	ds_write2st64_b32 v66, v65, v67 offset0:38 offset1:39
	v_mul_f32_e32 v65, v24, v64
	v_mul_f32_e32 v67, v25, v64
	ds_write2st64_b32 v66, v65, v67 offset0:40 offset1:41
	v_mul_f32_e32 v65, v26, v64
	v_mul_f32_e32 v67, v27, v64
	ds_write2st64_b32 v66, v65, v67 offset0:42 offset1:43
	v_mul_f32_e32 v65, v28, v64
	v_mul_f32_e32 v67, v29, v64
	ds_write2st64_b32 v66, v65, v67 offset0:44 offset1:45
	v_mul_f32_e32 v65, v30, v64
	v_mul_f32_e32 v67, v31, v64
	ds_write2st64_b32 v66, v65, v67 offset0:46 offset1:47
	v_mul_f32_e32 v65, v0, v64
	v_mul_f32_e32 v67, v1, v64
	ds_write2st64_b32 v66, v65, v67 offset0:48 offset1:49
	v_mul_f32_e32 v65, v2, v64
	v_mul_f32_e32 v67, v3, v64
	ds_write2st64_b32 v66, v65, v67 offset0:50 offset1:51
	v_mul_f32_e32 v65, v4, v64
	v_mul_f32_e32 v67, v5, v64
	ds_write2st64_b32 v66, v65, v67 offset0:52 offset1:53
	v_mul_f32_e32 v65, v6, v64
	v_mul_f32_e32 v67, v7, v64
	ds_write2st64_b32 v66, v65, v67 offset0:54 offset1:55
	v_mul_f32_e32 v65, v8, v64
	v_mul_f32_e32 v67, v9, v64
	ds_write2st64_b32 v66, v65, v67 offset0:56 offset1:57
	v_mul_f32_e32 v65, v10, v64
	v_mul_f32_e32 v67, v11, v64
	ds_write2st64_b32 v66, v65, v67 offset0:58 offset1:59
	v_mul_f32_e32 v65, v12, v64
	v_mul_f32_e32 v67, v13, v64
	ds_write2st64_b32 v66, v65, v67 offset0:60 offset1:61
	v_mul_f32_e32 v65, v14, v64
	v_mul_f32_e32 v67, v15, v64
	ds_write2st64_b32 v66, v65, v67 offset0:62 offset1:63
